# attention: complementary priority phases (query half 0 at prio 1 during softmax VALU, half 1 at prio 1 during MFMA/LDS)
# baseline (speedup 1.0000x reference)
.LBB0_789:
	v_exp_f32_e32 v37, v192
	v_exp_f32_e32 v38, v196
	v_exp_f32_e32 v39, v193
	v_exp_f32_e32 v196, v197
	v_exp_f32_e32 v193, v194
	v_exp_f32_e32 v194, v195
	v_cvt_pk_bf16_f32 v192, v37, v39
	v_exp_f32_e32 v37, v180
	v_exp_f32_e32 v39, v181
	v_cvt_pk_bf16_f32 v193, v193, v194
	v_cvt_pk_bf16_f32 v194, v38, v196
	v_exp_f32_e32 v38, v188
	v_exp_f32_e32 v188, v189
	v_exp_f32_e32 v181, v182
	v_exp_f32_e32 v182, v183
	v_exp_f32_e32 v197, v198
	v_exp_f32_e32 v195, v199
	v_cvt_pk_bf16_f32 v180, v37, v39
	v_cvt_pk_bf16_f32 v181, v181, v182
	v_cvt_pk_bf16_f32 v182, v38, v188
	v_exp_f32_e32 v37, v156
	v_exp_f32_e32 v38, v184
	v_exp_f32_e32 v39, v157
	v_exp_f32_e32 v184, v185
	v_exp_f32_e32 v157, v158
	v_exp_f32_e32 v158, v159
	s_mov_b32 s62, s60
	s_mov_b32 s63, s60
	v_cvt_pk_bf16_f32 v195, v197, v195
	s_mov_b32 s61, s60
	v_mov_b64_e32 v[198:199], s[62:63]
	v_mov_b64_e32 v[196:197], s[60:61]
	v_exp_f32_e32 v189, v190
	v_exp_f32_e32 v183, v191
	v_exp_f32_e32 v185, v186
	v_exp_f32_e32 v159, v187
	v_cvt_pk_bf16_f32 v156, v37, v39
	v_cvt_pk_bf16_f32 v157, v157, v158
	v_cvt_pk_bf16_f32 v158, v38, v184
	v_exp_f32_e32 v37, v152
	v_exp_f32_e32 v38, v172
	v_exp_f32_e32 v39, v153
	v_exp_f32_e32 v172, v173
	v_exp_f32_e32 v153, v154
	v_exp_f32_e32 v173, v174
	v_exp_f32_e32 v154, v155
	v_exp_f32_e32 v155, v175
	v_cvt_pk_bf16_f32 v183, v189, v183
	v_cvt_pk_bf16_f32 v159, v185, v159
	v_cvt_pk_bf16_f32 v152, v37, v39
	v_cvt_pk_bf16_f32 v153, v153, v154
	v_cvt_pk_bf16_f32 v154, v38, v172
	v_cvt_pk_bf16_f32 v155, v173, v155
	s_bitcmp1_b32 s46, 0
	s_cbranch_scc1 .Lpr1_m
	s_setprio 0
	s_branch .Lpr2_m
.Lpr1_m:
	s_setprio 1
.Lpr2_m:
	v_mfma_f32_16x16x32_bf16 v[116:119], v[196:199], v[192:195], v[116:119]
	v_subrev_u32_e32 v34, s73, v34
	v_add_u32_e32 v35, 0x1400, v35
	s_andn2_b64 vcc, exec, s[34:35]
	v_mfma_f32_16x16x32_bf16 v[64:67], v[196:199], v[180:183], v[64:67]
	v_mfma_f32_16x16x32_bf16 v[44:47], v[196:199], v[156:159], v[44:47]
	v_mfma_f32_16x16x32_bf16 v[16:19], v[196:199], v[152:155], v[16:19]
	s_waitcnt lgkmcnt(6)
	v_mfma_f32_16x16x32_bf16 v[96:99], v[168:171], v[192:195], v[96:99]
	v_mfma_f32_16x16x32_bf16 v[60:63], v[168:171], v[180:183], v[60:63]
	v_mfma_f32_16x16x32_bf16 v[40:43], v[168:171], v[156:159], v[40:43]
	v_mfma_f32_16x16x32_bf16 v[8:11], v[168:171], v[152:155], v[8:11]
	s_waitcnt lgkmcnt(4)
	v_mfma_f32_16x16x32_bf16 v[68:71], v[160:163], v[192:195], v[68:71]
	v_mfma_f32_16x16x32_bf16 v[48:51], v[160:163], v[180:183], v[48:51]
	v_mfma_f32_16x16x32_bf16 v[20:23], v[160:163], v[156:159], v[20:23]
	v_mfma_f32_16x16x32_bf16 v[0:3], v[160:163], v[152:155], v[0:3]
	s_waitcnt lgkmcnt(2)
	v_mfma_f32_16x16x32_bf16 v[92:95], v[176:179], v[192:195], v[92:95]
	v_mfma_f32_16x16x32_bf16 v[56:59], v[176:179], v[180:183], v[56:59]
	v_mfma_f32_16x16x32_bf16 v[28:31], v[176:179], v[156:159], v[28:31]
	v_mfma_f32_16x16x32_bf16 v[12:15], v[176:179], v[152:155], v[12:15]
	s_waitcnt lgkmcnt(0)
	v_mfma_f32_16x16x32_bf16 v[80:83], v[164:167], v[192:195], v[80:83]
	v_mfma_f32_16x16x32_bf16 v[52:55], v[164:167], v[180:183], v[52:55]
	v_mfma_f32_16x16x32_bf16 v[24:27], v[164:167], v[156:159], v[24:27]
	v_mfma_f32_16x16x32_bf16 v[4:7], v[164:167], v[152:155], v[4:7]
	s_cbranch_vccz .LBB0_801

.LBB0_792:
	s_bitcmp1_b32 s46, 0
	s_cbranch_scc1 .Lpr1_v
	s_setprio 1
	s_branch .Lpr2_v
.Lpr1_v:
	s_setprio 0

.LBB0_801:
	s_setprio 0
	s_andn2_b64 vcc, exec, s[74:75]
	s_xor_b32 s90, s90, 1
	s_cbranch_vccz .LBB0_803
	s_mov_b32 s16, s66
	s_mov_b32 s0, s91
	s_branch .LBB0_764
